# deferred layer-0 weight conversions in attention phase idle waves, those waves at s_setprio 3 so they finish quickly
# baseline (speedup 1.0000x reference)
; __device__ __forceinline__ void prologue(ArgsP a, const Ctx& c) {
;     ...
;     constexpr int N_MID = DEFER_PG0 - DEFER_LO, N_PRO = PER_LAYER + N_MID + (PER_LAYER - DEFER_PG1);
;     for (int j = c.gw; j < N_PRO; j += c.NGW) {
;         const int it = j < PER_LAYER ? j : (j < PER_LAYER + N_MID ? PER_LAYER + DEFER_LO + (j - PER_LAYER) : PER_LAYER + DEFER_PG1 + (j - PER_LAYER - N_MID));
;         convert_item(a, c, it, scr);
; __device__ __forceinline__ void attn_phase(const Ctx& c, ArgsP a, int l, int ctr_slot) {
;     unsigned* ctr0 = (unsigned*)(c.ws + WS_CTL) + 64 * ctr_slot;
;     const int myq = (int)(__builtin_amdgcn_s_getreg((3 << 11) | 20) & 7u);
;     for (int qi = 0; qi < 8; ++qi) {
;         const int q = (myq + qi) & 7;
;         unsigned* ctr = ctr0 + 64 * q;
;         for (;;) {
;             int t = 0;
;             if (c.lane == 0) t = (int)atomicAdd(ctr, 1u);
;             t = __builtin_amdgcn_readfirstlane(t);
;             if (t >= 448) break;
;             Ctx ct = c; { int ln = c.lane; asm volatile("" : "+v"(ln)); ct.lane = ln; }
;             int ll = l; asm volatile("" : "+s"(ll));
;             if (t >= 384) { const int f = (t - 384) * 8 + q; gla_final_task(ct, a, ll, f >> 5, f & 31); continue; }
;             const int grp = t / 192, u = t % 192, qt = 63 - u / 3, j = grp * 3 + u % 3, hh48 = j * 8 + q;
;             if (hh48 < 24) diff_task(ct, a, ll, hh48, qt); else moba_task(ct, hh48 - 24, qt);
;         }
;     }
; }
.Lattn_hi:
	v_readlane_b32 s2, v254, 53
	s_nop 3
	s_cmp_lg_u32 s2, 0
	s_cbranch_scc1 .LBB0_219
	s_setprio 3
	s_mov_b32 s32, 1
	v_readlane_b32 s0, v254, 13
	v_readlane_b32 s1, v254, 14
	s_nop 4
	s_movk_i32 s46, 0x5800
	s_movk_i32 s65, 0x78
	s_movk_i32 s70, 0x9200
	s_movk_i32 s75, 0x6040
	s_mov_b32 s92, 0x2c00000
	s_lshl_b32 s14, s76, 2
	s_add_i32 s14, s14, s4
	s_add_i32 s14, s14, -4
	v_lshlrev_b32_e32 v2, 3, v198
	v_readlane_b32 s2, v254, 62
	s_lshl_b32 s2, s2, 14
	v_lshrrev_b32_e32 v3, 5, v198
	v_and_b32_e32 v4, 31, v228
	s_add_i32 s2, s2, 0
	v_lshlrev_b32_e32 v0, 2, v4
	v_mul_u32_u24_e32 v5, 0x84, v3
	v_lshrrev_b32_e32 v7, 3, v198
	v_and_b32_e32 v6, 56, v2
	s_add_u32 s12, s48, 0x100000
	v_add3_u32 v5, s2, v0, v5
	v_mul_u32_u24_e32 v0, 0x84, v6
	v_lshlrev_b32_e32 v8, 2, v7
	s_addc_u32 s13, s49, 0
	v_add3_u32 v8, s2, v0, v8
	v_or_b32_e32 v9, 8, v7
	v_or_b32_e32 v10, 16, v7
	v_or_b32_e32 v11, 24, v7
	s_branch .LBB0_543

; #define LAS __attribute__((address_space(3)))
; __global__ void __launch_bounds__(NTHREADS, 2) fwd_megakernel(Args args) {
;     ...
;     for (int ph = ph_lo; ph < ph_hi; ++ph) {
;         if (ph > ph_lo && use_sync) {
;             if (use_sync == 2) grid.sync();
;             else xcd_barrier((unsigned*)(ap0->ws + WS_CTL) + 4096, (volatile LAS unsigned*)((LAS unsigned char*)lds_raw + 131072 + 512), gridDim.x);
;         }
;         const int ptype = (ph == 0) ? 15 : (ph - 1) % 14, nrep = 1 + ((dup_mask >> ptype) & 1);
;         for (int rep = 0; rep < nrep; ++rep) {
;         ArgsP ap = ap0; asm volatile("" : "+s"(ap));
;         int tid_ = threadIdx.x; asm volatile("" : "+v"(tid_));
;         unsigned char* ws = ap->ws;
;         int bid_ = blockIdx.x, G_ = gridDim.x; asm volatile("" : "+s"(bid_), "+s"(G_));
;         Ctx c; c.tid = tid_; c.lane = c.tid & 63; c.wave = __builtin_amdgcn_readfirstlane(c.tid >> 6); c.G = G_; c.bid = bid_;
;         c.gw = c.bid * NWAVES + c.wave; c.NGW = c.G * NWAVES; c.lds = (LAS unsigned char*)lds_raw; c.ws = ws;
;         float* X = (float*)(ws + WS_X); bf16_t* XB = (bf16_t*)(ws + WS_XB); bf16_t* HB = (bf16_t*)(ws + WS_H); float* E1 = (float*)(ws + WS_H);
;         bf16_t* PROJ = (bf16_t*)(ws + WS_PROJ); bf16_t* VT = (bf16_t*)(ws + WS_VT); bf16_t* MIX = (bf16_t*)(ws + WS_MIX); float* STATS = (float*)(ws + WS_GG + 512 * 1024);
.LBB0_219:
	s_setprio 0
	v_readlane_b32 s86, v254, 13
	s_mov_b64 s[4:5], 0
	v_readlane_b32 s72, v254, 12
	v_readlane_b32 s87, v254, 14
	v_readlane_b32 s73, v254, 15
	s_mov_b32 s88, 0x10000
	s_mov_b32 s89, 0xae00000
	s_mov_b32 s92, 0x2c00000
	s_movk_i32 s96, 0x1000
	s_mov_b32 s95, 0x16000
	s_movk_i32 s97, 0x3000
	v_readlane_b32 s63, v254, 55
	v_readlane_b32 s67, v255, 22
